# LDS-DMA 3-buffer rolled mainloops also on the input-projection and attention-output GEMMs (four sites total)
# speedup vs baseline: 1.0275x; 1.0070x over previous
.LBB0_238:
	v_add_co_u32_e32 v182, vcc, 0x800, v154
	s_nop 1
	v_addc_co_u32_e32 v183, vcc, 0, v155, vcc
	v_add_co_u32_e32 v204, vcc, s34, v182
	s_nop 1
	v_addc_co_u32_e32 v205, vcc, 0, v183, vcc
	v_add_co_u32_e32 v206, vcc, s35, v182
	s_nop 1
	v_addc_co_u32_e32 v207, vcc, 0, v183, vcc
	v_mov_b32_e32 v208, v152
	v_mov_b32_e32 v209, v153
	v_add_co_u32_e32 v210, vcc, s30, v152
	s_nop 1
	v_addc_co_u32_e32 v211, vcc, 0, v153, vcc
	v_add_co_u32_e32 v212, vcc, s29, v152
	s_nop 1
	v_addc_co_u32_e32 v213, vcc, 0, v153, vcc
	v_add_co_u32_e32 v214, vcc, s31, v152
	s_nop 1
	v_addc_co_u32_e32 v215, vcc, 0, v153, vcc
	v_and_b32_e32 v216, 3, v156
	v_bfe_u32 v217, v156, 4, 2
	v_xor_b32_e32 v218, v216, v217
	v_sub_u32_e32 v218, v218, v216
	v_lshlrev_b32_e32 v218, 4, v218
	v_ashrrev_i32_e32 v219, 31, v218
	v_lshl_add_u64 v[204:205], v[218:219], 0, v[204:205]
	v_lshl_add_u64 v[206:207], v[218:219], 0, v[206:207]
	v_lshl_add_u64 v[208:209], v[218:219], 0, v[208:209]
	v_lshl_add_u64 v[210:211], v[218:219], 0, v[210:211]
	v_lshl_add_u64 v[212:213], v[218:219], 0, v[212:213]
	v_lshl_add_u64 v[214:215], v[218:219], 0, v[214:215]
	v_mov_b32_e32 v216, 64
	v_mov_b32_e32 v217, 0
	v_lshl_add_u64 v[204:205], v[216:217], 1, v[204:205]
	v_lshl_add_u64 v[206:207], v[216:217], 1, v[206:207]
	v_lshl_add_u64 v[208:209], v[216:217], 1, v[208:209]
	v_lshl_add_u64 v[210:211], v[216:217], 1, v[210:211]
	v_lshl_add_u64 v[212:213], v[216:217], 1, v[212:213]
	v_lshl_add_u64 v[214:215], v[216:217], 1, v[214:215]
	v_lshrrev_b32_e32 v246, 6, v156
	v_lshlrev_b32_e32 v246, 10, v246
	s_nop 0
	v_readfirstlane_b32 s4, v246
	ds_read_b128 v[162:165], v160 offset:8192
	ds_read_b128 v[178:181], v159
	ds_read_b128 v[166:169], v160 offset:10240
	ds_read_b128 v[200:203], v159 offset:2048
	ds_read_b128 v[170:173], v160 offset:12288
	ds_read_b128 v[174:177], v160 offset:14336
	s_waitcnt lgkmcnt(4)
	v_mfma_f32_32x32x16_bf16 v[112:127], v[162:165], v[178:181], v[112:127]
	s_waitcnt lgkmcnt(3)
	v_mfma_f32_32x32x16_bf16 v[96:111], v[166:169], v[178:181], v[96:111]
	s_waitcnt lgkmcnt(1)
	v_mfma_f32_32x32x16_bf16 v[48:63], v[170:173], v[178:181], v[48:63]
	s_waitcnt lgkmcnt(0)
	v_mfma_f32_32x32x16_bf16 v[32:47], v[174:177], v[178:181], v[32:47]
	v_mfma_f32_32x32x16_bf16 v[80:95], v[162:165], v[200:203], v[80:95]
	v_mfma_f32_32x32x16_bf16 v[64:79], v[166:169], v[200:203], v[64:79]
	v_mfma_f32_32x32x16_bf16 v[16:31], v[170:173], v[200:203], v[16:31]
	v_mfma_f32_32x32x16_bf16 v[0:15], v[174:177], v[200:203], v[0:15]
	ds_read_b128 v[162:165], v157 offset:8192
	ds_read_b128 v[178:181], v158
	ds_read_b128 v[166:169], v157 offset:10240
	ds_read_b128 v[200:203], v158 offset:2048
	ds_read_b128 v[170:173], v157 offset:12288
	ds_read_b128 v[174:177], v157 offset:14336
	s_waitcnt vmcnt(5)
	ds_write_b128 v161, v[140:143] offset:24576
	s_waitcnt vmcnt(3)
	ds_write_b128 v161, v[148:151] offset:28672
	ds_write_b128 v161, v[128:131] offset:32768
	s_waitcnt vmcnt(2)
	ds_write_b128 v161, v[136:139] offset:36864
	s_waitcnt vmcnt(1)
	ds_write_b128 v161, v[132:135] offset:40960
	s_waitcnt vmcnt(0)
	ds_write_b128 v161, v[144:147] offset:45056
	s_add_u32 m0, s4, 0xc000
	s_nop 0
	global_load_lds_dwordx4 v[204:205], off
	v_lshl_add_u64 v[204:205], v[216:217], 0, v[204:205]
	s_add_u32 m0, s4, 0xd000
	s_nop 0
	global_load_lds_dwordx4 v[206:207], off
	v_lshl_add_u64 v[206:207], v[216:217], 0, v[206:207]
	s_add_u32 m0, s4, 0xe000
	s_nop 0
	global_load_lds_dwordx4 v[208:209], off
	v_lshl_add_u64 v[208:209], v[216:217], 0, v[208:209]
	s_add_u32 m0, s4, 0xf000
	s_nop 0
	global_load_lds_dwordx4 v[210:211], off
	v_lshl_add_u64 v[210:211], v[216:217], 0, v[210:211]
	s_add_u32 m0, s4, 0x10000
	s_nop 0
	global_load_lds_dwordx4 v[212:213], off
	v_lshl_add_u64 v[212:213], v[216:217], 0, v[212:213]
	s_add_u32 m0, s4, 0x11000
	s_nop 0
	global_load_lds_dwordx4 v[214:215], off
	v_lshl_add_u64 v[214:215], v[216:217], 0, v[214:215]
	s_waitcnt lgkmcnt(10)
	v_mfma_f32_32x32x16_bf16 v[112:127], v[162:165], v[178:181], v[112:127]
	s_waitcnt lgkmcnt(9)
	v_mfma_f32_32x32x16_bf16 v[96:111], v[166:169], v[178:181], v[96:111]
	s_waitcnt lgkmcnt(7)
	v_mfma_f32_32x32x16_bf16 v[48:63], v[170:173], v[178:181], v[48:63]
	s_waitcnt lgkmcnt(6)
	v_mfma_f32_32x32x16_bf16 v[32:47], v[174:177], v[178:181], v[32:47]
	v_mfma_f32_32x32x16_bf16 v[80:95], v[162:165], v[200:203], v[80:95]
	v_mfma_f32_32x32x16_bf16 v[64:79], v[166:169], v[200:203], v[64:79]
	v_mfma_f32_32x32x16_bf16 v[16:31], v[170:173], v[200:203], v[16:31]
	v_mfma_f32_32x32x16_bf16 v[0:15], v[174:177], v[200:203], v[0:15]
	s_waitcnt lgkmcnt(0)
	s_barrier
	s_mov_b32 s5, 0
.Lg1_dma_loop:
	ds_read_b128 v[162:165], v160 offset:32768
	ds_read_b128 v[178:181], v159 offset:24576
	ds_read_b128 v[166:169], v160 offset:34816
	ds_read_b128 v[200:203], v159 offset:26624
	ds_read_b128 v[170:173], v160 offset:36864
	ds_read_b128 v[174:177], v160 offset:38912
	ds_read_b128 v[128:131], v157 offset:32768
	ds_read_b128 v[132:135], v158 offset:24576
	ds_read_b128 v[136:139], v157 offset:34816
	ds_read_b128 v[144:147], v158 offset:26624
	ds_read_b128 v[140:143], v157 offset:36864
	ds_read_b128 v[148:151], v157 offset:38912
	s_waitcnt lgkmcnt(10)
	v_mfma_f32_32x32x16_bf16 v[112:127], v[162:165], v[178:181], v[112:127]
	s_mov_b32 m0, s4
	s_nop 0
	global_load_lds_dwordx4 v[204:205], off
	v_lshl_add_u64 v[204:205], v[216:217], 0, v[204:205]
	s_waitcnt lgkmcnt(9)
	v_mfma_f32_32x32x16_bf16 v[96:111], v[166:169], v[178:181], v[96:111]
	s_add_u32 m0, s4, 0x1000
	s_nop 0
	global_load_lds_dwordx4 v[206:207], off
	v_lshl_add_u64 v[206:207], v[216:217], 0, v[206:207]
	s_waitcnt lgkmcnt(7)
	v_mfma_f32_32x32x16_bf16 v[48:63], v[170:173], v[178:181], v[48:63]
	s_add_u32 m0, s4, 0x2000
	s_nop 0
	global_load_lds_dwordx4 v[208:209], off
	v_lshl_add_u64 v[208:209], v[216:217], 0, v[208:209]
	s_waitcnt lgkmcnt(6)
	v_mfma_f32_32x32x16_bf16 v[32:47], v[174:177], v[178:181], v[32:47]
	s_add_u32 m0, s4, 0x3000
	s_nop 0
	global_load_lds_dwordx4 v[210:211], off
	v_lshl_add_u64 v[210:211], v[216:217], 0, v[210:211]
	v_mfma_f32_32x32x16_bf16 v[80:95], v[162:165], v[200:203], v[80:95]
	s_add_u32 m0, s4, 0x4000
	s_nop 0
	global_load_lds_dwordx4 v[212:213], off
	v_lshl_add_u64 v[212:213], v[216:217], 0, v[212:213]
	v_mfma_f32_32x32x16_bf16 v[64:79], v[166:169], v[200:203], v[64:79]
	s_add_u32 m0, s4, 0x5000
	s_nop 0
	global_load_lds_dwordx4 v[214:215], off
	v_lshl_add_u64 v[214:215], v[216:217], 0, v[214:215]
	v_mfma_f32_32x32x16_bf16 v[16:31], v[170:173], v[200:203], v[16:31]
	v_mfma_f32_32x32x16_bf16 v[0:15], v[174:177], v[200:203], v[0:15]
	s_waitcnt lgkmcnt(4)
	v_mfma_f32_32x32x16_bf16 v[112:127], v[128:131], v[132:135], v[112:127]
	s_waitcnt lgkmcnt(3)
	v_mfma_f32_32x32x16_bf16 v[96:111], v[136:139], v[132:135], v[96:111]
	s_waitcnt lgkmcnt(1)
	v_mfma_f32_32x32x16_bf16 v[48:63], v[140:143], v[132:135], v[48:63]
	s_waitcnt lgkmcnt(0)
	v_mfma_f32_32x32x16_bf16 v[32:47], v[148:151], v[132:135], v[32:47]
	v_mfma_f32_32x32x16_bf16 v[80:95], v[128:131], v[144:147], v[80:95]
	v_mfma_f32_32x32x16_bf16 v[64:79], v[136:139], v[144:147], v[64:79]
	v_mfma_f32_32x32x16_bf16 v[16:31], v[140:143], v[144:147], v[16:31]
	v_mfma_f32_32x32x16_bf16 v[0:15], v[148:151], v[144:147], v[0:15]
	s_waitcnt vmcnt(6)
	s_waitcnt lgkmcnt(0)
	s_barrier
	ds_read_b128 v[162:165], v160 offset:57344
	ds_read_b128 v[178:181], v159 offset:49152
	ds_read_b128 v[166:169], v160 offset:59392
	ds_read_b128 v[200:203], v159 offset:51200
	ds_read_b128 v[170:173], v160 offset:61440
	ds_read_b128 v[174:177], v160 offset:63488
	ds_read_b128 v[128:131], v157 offset:57344
	ds_read_b128 v[132:135], v158 offset:49152
	ds_read_b128 v[136:139], v157 offset:59392
	ds_read_b128 v[144:147], v158 offset:51200
	ds_read_b128 v[140:143], v157 offset:61440
	ds_read_b128 v[148:151], v157 offset:63488
	s_waitcnt lgkmcnt(10)
	v_mfma_f32_32x32x16_bf16 v[112:127], v[162:165], v[178:181], v[112:127]
	s_add_u32 m0, s4, 0x6000
	s_nop 0
	global_load_lds_dwordx4 v[204:205], off
	v_lshl_add_u64 v[204:205], v[216:217], 0, v[204:205]
	s_waitcnt lgkmcnt(9)
	v_mfma_f32_32x32x16_bf16 v[96:111], v[166:169], v[178:181], v[96:111]
	s_add_u32 m0, s4, 0x7000
	s_nop 0
	global_load_lds_dwordx4 v[206:207], off
	v_lshl_add_u64 v[206:207], v[216:217], 0, v[206:207]
	s_waitcnt lgkmcnt(7)
	v_mfma_f32_32x32x16_bf16 v[48:63], v[170:173], v[178:181], v[48:63]
	s_add_u32 m0, s4, 0x8000
	s_nop 0
	global_load_lds_dwordx4 v[208:209], off
	v_lshl_add_u64 v[208:209], v[216:217], 0, v[208:209]
	s_waitcnt lgkmcnt(6)
	v_mfma_f32_32x32x16_bf16 v[32:47], v[174:177], v[178:181], v[32:47]
	s_add_u32 m0, s4, 0x9000
	s_nop 0
	global_load_lds_dwordx4 v[210:211], off
	v_lshl_add_u64 v[210:211], v[216:217], 0, v[210:211]
	v_mfma_f32_32x32x16_bf16 v[80:95], v[162:165], v[200:203], v[80:95]
	s_add_u32 m0, s4, 0xa000
	s_nop 0
	global_load_lds_dwordx4 v[212:213], off
	v_lshl_add_u64 v[212:213], v[216:217], 0, v[212:213]
	v_mfma_f32_32x32x16_bf16 v[64:79], v[166:169], v[200:203], v[64:79]
	s_add_u32 m0, s4, 0xb000
	s_nop 0
	global_load_lds_dwordx4 v[214:215], off
	v_lshl_add_u64 v[214:215], v[216:217], 0, v[214:215]
	v_mfma_f32_32x32x16_bf16 v[16:31], v[170:173], v[200:203], v[16:31]
	v_mfma_f32_32x32x16_bf16 v[0:15], v[174:177], v[200:203], v[0:15]
	s_waitcnt lgkmcnt(4)
	v_mfma_f32_32x32x16_bf16 v[112:127], v[128:131], v[132:135], v[112:127]
	s_waitcnt lgkmcnt(3)
	v_mfma_f32_32x32x16_bf16 v[96:111], v[136:139], v[132:135], v[96:111]
	s_waitcnt lgkmcnt(1)
	v_mfma_f32_32x32x16_bf16 v[48:63], v[140:143], v[132:135], v[48:63]
	s_waitcnt lgkmcnt(0)
	v_mfma_f32_32x32x16_bf16 v[32:47], v[148:151], v[132:135], v[32:47]
	v_mfma_f32_32x32x16_bf16 v[80:95], v[128:131], v[144:147], v[80:95]
	v_mfma_f32_32x32x16_bf16 v[64:79], v[136:139], v[144:147], v[64:79]
	v_mfma_f32_32x32x16_bf16 v[16:31], v[140:143], v[144:147], v[16:31]
	v_mfma_f32_32x32x16_bf16 v[0:15], v[148:151], v[144:147], v[0:15]
	s_waitcnt vmcnt(6)
	s_waitcnt lgkmcnt(0)
	s_barrier
	ds_read_b128 v[162:165], v160 offset:8192
	ds_read_b128 v[178:181], v159
	ds_read_b128 v[166:169], v160 offset:10240
	ds_read_b128 v[200:203], v159 offset:2048
	ds_read_b128 v[170:173], v160 offset:12288
	ds_read_b128 v[174:177], v160 offset:14336
	ds_read_b128 v[128:131], v157 offset:8192
	ds_read_b128 v[132:135], v158
	ds_read_b128 v[136:139], v157 offset:10240
	ds_read_b128 v[144:147], v158 offset:2048
	ds_read_b128 v[140:143], v157 offset:12288
	ds_read_b128 v[148:151], v157 offset:14336
	s_waitcnt lgkmcnt(10)
	v_mfma_f32_32x32x16_bf16 v[112:127], v[162:165], v[178:181], v[112:127]
	s_add_u32 m0, s4, 0xc000
	s_nop 0
	global_load_lds_dwordx4 v[204:205], off
	v_lshl_add_u64 v[204:205], v[216:217], 0, v[204:205]
	s_waitcnt lgkmcnt(9)
	v_mfma_f32_32x32x16_bf16 v[96:111], v[166:169], v[178:181], v[96:111]
	s_add_u32 m0, s4, 0xd000
	s_nop 0
	global_load_lds_dwordx4 v[206:207], off
	v_lshl_add_u64 v[206:207], v[216:217], 0, v[206:207]
	s_waitcnt lgkmcnt(7)
	v_mfma_f32_32x32x16_bf16 v[48:63], v[170:173], v[178:181], v[48:63]
	s_add_u32 m0, s4, 0xe000
	s_nop 0
	global_load_lds_dwordx4 v[208:209], off
	v_lshl_add_u64 v[208:209], v[216:217], 0, v[208:209]
	s_waitcnt lgkmcnt(6)
	v_mfma_f32_32x32x16_bf16 v[32:47], v[174:177], v[178:181], v[32:47]
	s_add_u32 m0, s4, 0xf000
	s_nop 0
	global_load_lds_dwordx4 v[210:211], off
	v_lshl_add_u64 v[210:211], v[216:217], 0, v[210:211]
	v_mfma_f32_32x32x16_bf16 v[80:95], v[162:165], v[200:203], v[80:95]
	s_add_u32 m0, s4, 0x10000
	s_nop 0
	global_load_lds_dwordx4 v[212:213], off
	v_lshl_add_u64 v[212:213], v[216:217], 0, v[212:213]
	v_mfma_f32_32x32x16_bf16 v[64:79], v[166:169], v[200:203], v[64:79]
	s_add_u32 m0, s4, 0x11000
	s_nop 0
	global_load_lds_dwordx4 v[214:215], off
	v_lshl_add_u64 v[214:215], v[216:217], 0, v[214:215]
	v_mfma_f32_32x32x16_bf16 v[16:31], v[170:173], v[200:203], v[16:31]
	v_mfma_f32_32x32x16_bf16 v[0:15], v[174:177], v[200:203], v[0:15]
	s_waitcnt lgkmcnt(4)
	v_mfma_f32_32x32x16_bf16 v[112:127], v[128:131], v[132:135], v[112:127]
	s_waitcnt lgkmcnt(3)
	v_mfma_f32_32x32x16_bf16 v[96:111], v[136:139], v[132:135], v[96:111]
	s_waitcnt lgkmcnt(1)
	v_mfma_f32_32x32x16_bf16 v[48:63], v[140:143], v[132:135], v[48:63]
	s_waitcnt lgkmcnt(0)
	v_mfma_f32_32x32x16_bf16 v[32:47], v[148:151], v[132:135], v[32:47]
	v_mfma_f32_32x32x16_bf16 v[80:95], v[128:131], v[144:147], v[80:95]
	v_mfma_f32_32x32x16_bf16 v[64:79], v[136:139], v[144:147], v[64:79]
	v_mfma_f32_32x32x16_bf16 v[16:31], v[140:143], v[144:147], v[16:31]
	v_mfma_f32_32x32x16_bf16 v[0:15], v[148:151], v[144:147], v[0:15]
	s_waitcnt vmcnt(6)
	s_waitcnt lgkmcnt(0)
	s_barrier
	s_add_u32 s5, s5, 1
	s_cmp_lg_u32 s5, 9
	s_cbranch_scc1 .Lg1_dma_loop
	ds_read_b128 v[162:165], v160 offset:32768
	ds_read_b128 v[178:181], v159 offset:24576
	ds_read_b128 v[166:169], v160 offset:34816
	ds_read_b128 v[200:203], v159 offset:26624
	ds_read_b128 v[170:173], v160 offset:36864
	ds_read_b128 v[174:177], v160 offset:38912
	ds_read_b128 v[128:131], v157 offset:32768
	ds_read_b128 v[132:135], v158 offset:24576
	ds_read_b128 v[136:139], v157 offset:34816
	ds_read_b128 v[144:147], v158 offset:26624
	ds_read_b128 v[140:143], v157 offset:36864
	ds_read_b128 v[148:151], v157 offset:38912
	s_waitcnt lgkmcnt(10)
	v_mfma_f32_32x32x16_bf16 v[112:127], v[162:165], v[178:181], v[112:127]
	s_mov_b32 m0, s4
	s_nop 0
	global_load_lds_dwordx4 v[204:205], off
	v_lshl_add_u64 v[204:205], v[216:217], 0, v[204:205]
	s_waitcnt lgkmcnt(9)
	v_mfma_f32_32x32x16_bf16 v[96:111], v[166:169], v[178:181], v[96:111]
	s_add_u32 m0, s4, 0x1000
	s_nop 0
	global_load_lds_dwordx4 v[206:207], off
	v_lshl_add_u64 v[206:207], v[216:217], 0, v[206:207]
	s_waitcnt lgkmcnt(7)
	v_mfma_f32_32x32x16_bf16 v[48:63], v[170:173], v[178:181], v[48:63]
	s_add_u32 m0, s4, 0x2000
	s_nop 0
	global_load_lds_dwordx4 v[208:209], off
	v_lshl_add_u64 v[208:209], v[216:217], 0, v[208:209]
	s_waitcnt lgkmcnt(6)
	v_mfma_f32_32x32x16_bf16 v[32:47], v[174:177], v[178:181], v[32:47]
	s_add_u32 m0, s4, 0x3000
	s_nop 0
	global_load_lds_dwordx4 v[210:211], off
	v_lshl_add_u64 v[210:211], v[216:217], 0, v[210:211]
	v_mfma_f32_32x32x16_bf16 v[80:95], v[162:165], v[200:203], v[80:95]
	s_add_u32 m0, s4, 0x4000
	s_nop 0
	global_load_lds_dwordx4 v[212:213], off
	v_lshl_add_u64 v[212:213], v[216:217], 0, v[212:213]
	v_mfma_f32_32x32x16_bf16 v[64:79], v[166:169], v[200:203], v[64:79]
	s_add_u32 m0, s4, 0x5000
	s_nop 0
	global_load_lds_dwordx4 v[214:215], off
	v_lshl_add_u64 v[214:215], v[216:217], 0, v[214:215]
	v_mfma_f32_32x32x16_bf16 v[16:31], v[170:173], v[200:203], v[16:31]
	v_mfma_f32_32x32x16_bf16 v[0:15], v[174:177], v[200:203], v[0:15]
	s_waitcnt lgkmcnt(4)
	v_mfma_f32_32x32x16_bf16 v[112:127], v[128:131], v[132:135], v[112:127]
	s_waitcnt lgkmcnt(3)
	v_mfma_f32_32x32x16_bf16 v[96:111], v[136:139], v[132:135], v[96:111]
	s_waitcnt lgkmcnt(1)
	v_mfma_f32_32x32x16_bf16 v[48:63], v[140:143], v[132:135], v[48:63]
	s_waitcnt lgkmcnt(0)
	v_mfma_f32_32x32x16_bf16 v[32:47], v[148:151], v[132:135], v[32:47]
	v_mfma_f32_32x32x16_bf16 v[80:95], v[128:131], v[144:147], v[80:95]
	v_mfma_f32_32x32x16_bf16 v[64:79], v[136:139], v[144:147], v[64:79]
	v_mfma_f32_32x32x16_bf16 v[16:31], v[140:143], v[144:147], v[16:31]
	v_mfma_f32_32x32x16_bf16 v[0:15], v[148:151], v[144:147], v[0:15]
	s_waitcnt vmcnt(6)
	s_waitcnt lgkmcnt(0)
	s_barrier
	ds_read_b128 v[162:165], v160 offset:57344
	ds_read_b128 v[178:181], v159 offset:49152
	ds_read_b128 v[166:169], v160 offset:59392
	ds_read_b128 v[200:203], v159 offset:51200
	ds_read_b128 v[170:173], v160 offset:61440
	ds_read_b128 v[174:177], v160 offset:63488
	ds_read_b128 v[128:131], v157 offset:57344
	ds_read_b128 v[132:135], v158 offset:49152
	ds_read_b128 v[136:139], v157 offset:59392
	ds_read_b128 v[144:147], v158 offset:51200
	ds_read_b128 v[140:143], v157 offset:61440
	ds_read_b128 v[148:151], v157 offset:63488
	s_waitcnt lgkmcnt(10)
	v_mfma_f32_32x32x16_bf16 v[112:127], v[162:165], v[178:181], v[112:127]
	s_add_u32 m0, s4, 0x6000
	s_nop 0
	global_load_lds_dwordx4 v[204:205], off
	v_lshl_add_u64 v[204:205], v[216:217], 0, v[204:205]
	s_waitcnt lgkmcnt(9)
	v_mfma_f32_32x32x16_bf16 v[96:111], v[166:169], v[178:181], v[96:111]
	s_add_u32 m0, s4, 0x7000
	s_nop 0
	global_load_lds_dwordx4 v[206:207], off
	v_lshl_add_u64 v[206:207], v[216:217], 0, v[206:207]
	s_waitcnt lgkmcnt(7)
	v_mfma_f32_32x32x16_bf16 v[48:63], v[170:173], v[178:181], v[48:63]
	s_add_u32 m0, s4, 0x8000
	s_nop 0
	global_load_lds_dwordx4 v[208:209], off
	v_lshl_add_u64 v[208:209], v[216:217], 0, v[208:209]
	s_waitcnt lgkmcnt(6)
	v_mfma_f32_32x32x16_bf16 v[32:47], v[174:177], v[178:181], v[32:47]
	s_add_u32 m0, s4, 0x9000
	s_nop 0
	global_load_lds_dwordx4 v[210:211], off
	v_lshl_add_u64 v[210:211], v[216:217], 0, v[210:211]
	v_mfma_f32_32x32x16_bf16 v[80:95], v[162:165], v[200:203], v[80:95]
	s_add_u32 m0, s4, 0xa000
	s_nop 0
	global_load_lds_dwordx4 v[212:213], off
	v_lshl_add_u64 v[212:213], v[216:217], 0, v[212:213]
	v_mfma_f32_32x32x16_bf16 v[64:79], v[166:169], v[200:203], v[64:79]
	s_add_u32 m0, s4, 0xb000
	s_nop 0
	global_load_lds_dwordx4 v[214:215], off
	v_lshl_add_u64 v[214:215], v[216:217], 0, v[214:215]
	v_mfma_f32_32x32x16_bf16 v[16:31], v[170:173], v[200:203], v[16:31]
	v_mfma_f32_32x32x16_bf16 v[0:15], v[174:177], v[200:203], v[0:15]
	s_waitcnt lgkmcnt(4)
	v_mfma_f32_32x32x16_bf16 v[112:127], v[128:131], v[132:135], v[112:127]
	s_waitcnt lgkmcnt(3)
	v_mfma_f32_32x32x16_bf16 v[96:111], v[136:139], v[132:135], v[96:111]
	s_waitcnt lgkmcnt(1)
	v_mfma_f32_32x32x16_bf16 v[48:63], v[140:143], v[132:135], v[48:63]
	s_waitcnt lgkmcnt(0)
	v_mfma_f32_32x32x16_bf16 v[32:47], v[148:151], v[132:135], v[32:47]
	v_mfma_f32_32x32x16_bf16 v[80:95], v[128:131], v[144:147], v[80:95]
	v_mfma_f32_32x32x16_bf16 v[64:79], v[136:139], v[144:147], v[64:79]
	v_mfma_f32_32x32x16_bf16 v[16:31], v[140:143], v[144:147], v[16:31]
	v_mfma_f32_32x32x16_bf16 v[0:15], v[148:151], v[144:147], v[0:15]
	s_waitcnt vmcnt(6)
	s_waitcnt lgkmcnt(0)
	s_barrier
	ds_read_b128 v[162:165], v160 offset:8192
	ds_read_b128 v[178:181], v159
	ds_read_b128 v[166:169], v160 offset:10240
	ds_read_b128 v[200:203], v159 offset:2048
	ds_read_b128 v[170:173], v160 offset:12288
	ds_read_b128 v[174:177], v160 offset:14336
	ds_read_b128 v[128:131], v157 offset:8192
	ds_read_b128 v[132:135], v158
	ds_read_b128 v[136:139], v157 offset:10240
	ds_read_b128 v[144:147], v158 offset:2048
	ds_read_b128 v[140:143], v157 offset:12288
	ds_read_b128 v[148:151], v157 offset:14336
	s_waitcnt lgkmcnt(10)
	v_mfma_f32_32x32x16_bf16 v[112:127], v[162:165], v[178:181], v[112:127]
	s_waitcnt lgkmcnt(9)
	v_mfma_f32_32x32x16_bf16 v[96:111], v[166:169], v[178:181], v[96:111]
	s_waitcnt lgkmcnt(7)
	v_mfma_f32_32x32x16_bf16 v[48:63], v[170:173], v[178:181], v[48:63]
	s_waitcnt lgkmcnt(6)
	v_mfma_f32_32x32x16_bf16 v[32:47], v[174:177], v[178:181], v[32:47]
	v_mfma_f32_32x32x16_bf16 v[80:95], v[162:165], v[200:203], v[80:95]
	v_mfma_f32_32x32x16_bf16 v[64:79], v[166:169], v[200:203], v[64:79]
	v_mfma_f32_32x32x16_bf16 v[16:31], v[170:173], v[200:203], v[16:31]
	v_mfma_f32_32x32x16_bf16 v[0:15], v[174:177], v[200:203], v[0:15]
	s_waitcnt lgkmcnt(4)
	v_mfma_f32_32x32x16_bf16 v[112:127], v[128:131], v[132:135], v[112:127]
	s_waitcnt lgkmcnt(3)
	v_mfma_f32_32x32x16_bf16 v[96:111], v[136:139], v[132:135], v[96:111]
	s_waitcnt lgkmcnt(1)
	v_mfma_f32_32x32x16_bf16 v[48:63], v[140:143], v[132:135], v[48:63]
	s_waitcnt lgkmcnt(0)
	v_mfma_f32_32x32x16_bf16 v[32:47], v[148:151], v[132:135], v[32:47]
	v_mfma_f32_32x32x16_bf16 v[80:95], v[128:131], v[144:147], v[80:95]
	v_mfma_f32_32x32x16_bf16 v[64:79], v[136:139], v[144:147], v[64:79]
	v_mfma_f32_32x32x16_bf16 v[16:31], v[140:143], v[144:147], v[16:31]
	v_mfma_f32_32x32x16_bf16 v[0:15], v[148:151], v[144:147], v[0:15]
	s_waitcnt vmcnt(0)
	s_waitcnt lgkmcnt(0)
	s_barrier
	ds_read_b128 v[162:165], v160 offset:32768
	ds_read_b128 v[178:181], v159 offset:24576
	ds_read_b128 v[166:169], v160 offset:34816
	ds_read_b128 v[200:203], v159 offset:26624
	ds_read_b128 v[170:173], v160 offset:36864
	ds_read_b128 v[174:177], v160 offset:38912
	ds_read_b128 v[128:131], v157 offset:32768
	ds_read_b128 v[132:135], v158 offset:24576
	ds_read_b128 v[136:139], v157 offset:34816
	ds_read_b128 v[144:147], v158 offset:26624
	ds_read_b128 v[140:143], v157 offset:36864
	ds_read_b128 v[148:151], v157 offset:38912
	s_waitcnt lgkmcnt(10)
	v_mfma_f32_32x32x16_bf16 v[112:127], v[162:165], v[178:181], v[112:127]
	s_waitcnt lgkmcnt(9)
	v_mfma_f32_32x32x16_bf16 v[96:111], v[166:169], v[178:181], v[96:111]
	s_waitcnt lgkmcnt(7)
	v_mfma_f32_32x32x16_bf16 v[48:63], v[170:173], v[178:181], v[48:63]
	s_waitcnt lgkmcnt(6)
	v_mfma_f32_32x32x16_bf16 v[32:47], v[174:177], v[178:181], v[32:47]
	v_mfma_f32_32x32x16_bf16 v[80:95], v[162:165], v[200:203], v[80:95]
	v_mfma_f32_32x32x16_bf16 v[64:79], v[166:169], v[200:203], v[64:79]
	v_mfma_f32_32x32x16_bf16 v[16:31], v[170:173], v[200:203], v[16:31]
	v_mfma_f32_32x32x16_bf16 v[0:15], v[174:177], v[200:203], v[0:15]
	s_lshl_b32 s18, s18, 8
	s_movk_i32 s4, 0xec0
	s_cmpk_gt_u32 s18, 0x5ff
	s_cselect_b64 s[68:69], -1, 0
	s_cmpk_gt_u32 s18, 0x7ff
	s_cselect_b64 s[66:67], -1, 0
	s_cmpk_gt_u32 s18, 0x9ff
	s_cselect_b64 s[64:65], -1, 0
	v_and_b32_e32 v197, 31, v156
	v_bfe_u32 v195, v156, 5, 1
	v_lshlrev_b32_e32 v152, 1, v156
	v_and_b32_e32 v152, 0x80, v152
	v_or_b32_e32 v160, s18, v152
	v_cmp_gt_i32_e32 vcc, s4, v160
	s_movk_i32 s4, 0xe7f
	v_cmp_lt_u32_e64 s[62:63], s4, v160
	s_movk_i32 s4, 0xd7f
	v_cmp_lt_u32_e64 s[60:61], s4, v160
	s_movk_i32 s4, 0xd80
	v_cmp_gt_u32_e64 s[42:43], s4, v160
	v_readlane_b32 s4, v254, 28
	v_readlane_b32 s5, v254, 29
	s_nop 1
	v_cndmask_b32_e64 v190, 24, 0, s[42:43]
	v_mov_b32_e32 v161, v191
	v_lshl_add_u64 v[168:169], s[4:5], 0, v[190:191]
	v_cndmask_b32_e64 v164, v232, v233, s[42:43]
	v_ashrrev_i32_e32 v163, 31, v160
	v_mov_b32_e32 v162, v160
	s_cmpk_gt_u32 s18, 0xbff
	s_waitcnt lgkmcnt(0)
	s_barrier
	v_mfma_f32_32x32x16_bf16 v[112:127], v[128:131], v[132:135], v[112:127]
	v_mfma_f32_32x32x16_bf16 v[96:111], v[136:139], v[132:135], v[96:111]
	v_mfma_f32_32x32x16_bf16 v[48:63], v[140:143], v[132:135], v[48:63]
	v_mfma_f32_32x32x16_bf16 v[32:47], v[148:151], v[132:135], v[32:47]
	v_ashrrev_i32_e32 v132, 1, v156
	v_and_b32_e32 v132, 0xffffffc0, v132
	v_add_u32_e32 v199, s14, v132
	s_cselect_b64 s[14:15], -1, 0
	s_cmpk_gt_u32 s18, 0x6ff
	s_cselect_b64 s[4:5], -1, 0
	s_cmpk_lt_u32 s18, 0x700
	v_mfma_f32_32x32x16_bf16 v[80:95], v[128:131], v[144:147], v[80:95]
	v_cndmask_b32_e64 v128, v234, v235, s[42:43]
	v_mul_lo_u32 v166, v128, s2
	v_ashrrev_i32_e32 v167, 31, v166
	s_cselect_b64 s[18:19], -1, 0
	v_mfma_f32_32x32x16_bf16 v[64:79], v[136:139], v[144:147], v[64:79]
	v_mfma_f32_32x32x16_bf16 v[16:31], v[140:143], v[144:147], v[16:31]
	v_mfma_f32_32x32x16_bf16 v[0:15], v[148:151], v[144:147], v[0:15]
	s_and_saveexec_b64 s[56:57], vcc
	s_cbranch_execz .LBB0_377
	v_mov_b32_e32 v128, v197
	v_mov_b32_e32 v165, v195
	s_movk_i32 s20, 0x4000
	v_add_u32_e32 v178, v128, v199
	v_cmp_gt_i32_e64 s[54:55], s20, v178
	v_cmp_lt_i32_e64 s[52:53], s45, v178
	s_and_saveexec_b64 s[20:21], s[52:53]
	s_xor_b64 s[20:21], exec, s[20:21]
	v_add_u32_e32 v128, 0xffffc000, v178
	v_lshrrev_b32_e32 v182, 8, v128
	v_and_b32_e32 v180, 0xff, v178
	v_add_u32_e32 v140, 0x800, v178
	s_or_saveexec_b64 s[20:21], s[20:21]
	v_mov_b64_e32 v[200:201], 0
	s_xor_b64 exec, exec, s[20:21]
	s_cbranch_execz .LBB0_244
	v_readlane_b32 s22, v255, 48
	v_and_b32_e32 v180, 0xfff, v178
	v_ashrrev_i32_e32 v200, 12, v178
	v_add_u32_e32 v128, s22, v178
	s_movk_i32 s22, 0x1200
	v_ashrrev_i32_e32 v182, 12, v128
	v_mad_i32_i24 v140, v200, s22, v180
	v_ashrrev_i32_e32 v201, 31, v200

.LBB0_927:
	v_add_co_u32_e32 v182, vcc, 0x800, v152
	s_nop 1
	v_addc_co_u32_e32 v183, vcc, 0, v153, vcc
	v_add_co_u32_e32 v204, vcc, s95, v182
	s_nop 1
	v_addc_co_u32_e32 v205, vcc, 0, v183, vcc
	v_add_co_u32_e32 v206, vcc, s96, v182
	s_nop 1
	v_addc_co_u32_e32 v207, vcc, 0, v183, vcc
	v_add_co_u32_e32 v208, vcc, s97, v154
	s_nop 1
	v_addc_co_u32_e32 v209, vcc, 0, v155, vcc
	v_add_co_u32_e32 v210, vcc, s10, v154
	s_nop 1
	v_addc_co_u32_e32 v211, vcc, 0, v155, vcc
	v_add_co_u32_e32 v212, vcc, 0x1322000, v154
	s_nop 1
	v_addc_co_u32_e32 v213, vcc, 0, v155, vcc
	v_add_co_u32_e32 v214, vcc, 0x1344000, v154
	s_nop 1
	v_addc_co_u32_e32 v215, vcc, 0, v155, vcc
	v_and_b32_e32 v216, 3, v156
	v_bfe_u32 v217, v156, 4, 2
	v_xor_b32_e32 v218, v216, v217
	v_sub_u32_e32 v218, v218, v216
	v_lshlrev_b32_e32 v218, 4, v218
	v_ashrrev_i32_e32 v219, 31, v218
	v_lshl_add_u64 v[204:205], v[218:219], 0, v[204:205]
	v_lshl_add_u64 v[206:207], v[218:219], 0, v[206:207]
	v_lshl_add_u64 v[208:209], v[218:219], 0, v[208:209]
	v_lshl_add_u64 v[210:211], v[218:219], 0, v[210:211]
	v_lshl_add_u64 v[212:213], v[218:219], 0, v[212:213]
	v_lshl_add_u64 v[214:215], v[218:219], 0, v[214:215]
	v_mov_b32_e32 v216, 64
	v_mov_b32_e32 v217, 0
	v_lshl_add_u64 v[204:205], v[216:217], 1, v[204:205]
	v_lshl_add_u64 v[206:207], v[216:217], 1, v[206:207]
	v_lshl_add_u64 v[208:209], v[216:217], 1, v[208:209]
	v_lshl_add_u64 v[210:211], v[216:217], 1, v[210:211]
	v_lshl_add_u64 v[212:213], v[216:217], 1, v[212:213]
	v_lshl_add_u64 v[214:215], v[216:217], 1, v[214:215]
	v_lshrrev_b32_e32 v246, 6, v156
	v_lshlrev_b32_e32 v246, 10, v246
	s_nop 0
	v_readfirstlane_b32 s20, v246
	ds_read_b128 v[162:165], v157 offset:8192
	ds_read_b128 v[178:181], v161
	ds_read_b128 v[166:169], v157 offset:10240
	ds_read_b128 v[200:203], v161 offset:2048
	ds_read_b128 v[170:173], v157 offset:12288
	ds_read_b128 v[174:177], v157 offset:14336
	s_waitcnt lgkmcnt(4)
	v_mfma_f32_32x32x16_bf16 v[112:127], v[162:165], v[178:181], v[112:127]
	s_waitcnt lgkmcnt(3)
	v_mfma_f32_32x32x16_bf16 v[96:111], v[166:169], v[178:181], v[96:111]
	s_waitcnt lgkmcnt(1)
	v_mfma_f32_32x32x16_bf16 v[80:95], v[170:173], v[178:181], v[80:95]
	s_waitcnt lgkmcnt(0)
	v_mfma_f32_32x32x16_bf16 v[64:79], v[174:177], v[178:181], v[64:79]
	v_mfma_f32_32x32x16_bf16 v[48:63], v[162:165], v[200:203], v[48:63]
	v_mfma_f32_32x32x16_bf16 v[32:47], v[166:169], v[200:203], v[32:47]
	v_mfma_f32_32x32x16_bf16 v[16:31], v[170:173], v[200:203], v[16:31]
	v_mfma_f32_32x32x16_bf16 v[0:15], v[174:177], v[200:203], v[0:15]
	ds_read_b128 v[162:165], v159 offset:8192
	ds_read_b128 v[178:181], v158
	ds_read_b128 v[166:169], v159 offset:10240
	ds_read_b128 v[200:203], v158 offset:2048
	ds_read_b128 v[170:173], v159 offset:12288
	ds_read_b128 v[174:177], v159 offset:14336
	s_waitcnt vmcnt(5)
	ds_write_b128 v160, v[144:147] offset:24576
	s_waitcnt vmcnt(4)
	ds_write_b128 v160, v[148:151] offset:28672
	s_waitcnt vmcnt(3)
	ds_write_b128 v160, v[140:143] offset:32768
	s_waitcnt vmcnt(2)
	ds_write_b128 v160, v[136:139] offset:36864
	s_waitcnt vmcnt(1)
	ds_write_b128 v160, v[132:135] offset:40960
	s_waitcnt vmcnt(0)
	ds_write_b128 v160, v[128:131] offset:45056
	s_add_u32 m0, s20, 0xc000
	s_nop 0
	global_load_lds_dwordx4 v[204:205], off
	v_lshl_add_u64 v[204:205], v[216:217], 0, v[204:205]
	s_add_u32 m0, s20, 0xd000
	s_nop 0
	global_load_lds_dwordx4 v[206:207], off
	v_lshl_add_u64 v[206:207], v[216:217], 0, v[206:207]
	s_add_u32 m0, s20, 0xe000
	s_nop 0
	global_load_lds_dwordx4 v[208:209], off
	v_lshl_add_u64 v[208:209], v[216:217], 0, v[208:209]
	s_add_u32 m0, s20, 0xf000
	s_nop 0
	global_load_lds_dwordx4 v[210:211], off
	v_lshl_add_u64 v[210:211], v[216:217], 0, v[210:211]
	s_add_u32 m0, s20, 0x10000
	s_nop 0
	global_load_lds_dwordx4 v[212:213], off
	v_lshl_add_u64 v[212:213], v[216:217], 0, v[212:213]
	s_add_u32 m0, s20, 0x11000
	s_nop 0
	global_load_lds_dwordx4 v[214:215], off
	v_lshl_add_u64 v[214:215], v[216:217], 0, v[214:215]
	s_waitcnt lgkmcnt(10)
	v_mfma_f32_32x32x16_bf16 v[112:127], v[162:165], v[178:181], v[112:127]
	s_waitcnt lgkmcnt(9)
	v_mfma_f32_32x32x16_bf16 v[96:111], v[166:169], v[178:181], v[96:111]
	s_waitcnt lgkmcnt(7)
	v_mfma_f32_32x32x16_bf16 v[80:95], v[170:173], v[178:181], v[80:95]
	s_waitcnt lgkmcnt(6)
	v_mfma_f32_32x32x16_bf16 v[64:79], v[174:177], v[178:181], v[64:79]
	v_mfma_f32_32x32x16_bf16 v[48:63], v[162:165], v[200:203], v[48:63]
	v_mfma_f32_32x32x16_bf16 v[32:47], v[166:169], v[200:203], v[32:47]
	v_mfma_f32_32x32x16_bf16 v[16:31], v[170:173], v[200:203], v[16:31]
	v_mfma_f32_32x32x16_bf16 v[0:15], v[174:177], v[200:203], v[0:15]
	s_waitcnt lgkmcnt(0)
	s_barrier
	s_mov_b32 s18, 0
.Lr0_dma_loop:
	ds_read_b128 v[162:165], v157 offset:32768
	ds_read_b128 v[178:181], v161 offset:24576
	ds_read_b128 v[166:169], v157 offset:34816
	ds_read_b128 v[200:203], v161 offset:26624
	ds_read_b128 v[170:173], v157 offset:36864
	ds_read_b128 v[174:177], v157 offset:38912
	ds_read_b128 v[128:131], v159 offset:32768
	ds_read_b128 v[148:151], v158 offset:24576
	ds_read_b128 v[136:139], v159 offset:34816
	ds_read_b128 v[132:135], v158 offset:26624
	ds_read_b128 v[140:143], v159 offset:36864
	ds_read_b128 v[144:147], v159 offset:38912
	s_waitcnt lgkmcnt(10)
	v_mfma_f32_32x32x16_bf16 v[112:127], v[162:165], v[178:181], v[112:127]
	s_mov_b32 m0, s20
	s_nop 0
	global_load_lds_dwordx4 v[204:205], off
	v_lshl_add_u64 v[204:205], v[216:217], 0, v[204:205]
	s_waitcnt lgkmcnt(9)
	v_mfma_f32_32x32x16_bf16 v[96:111], v[166:169], v[178:181], v[96:111]
	s_add_u32 m0, s20, 0x1000
	s_nop 0
	global_load_lds_dwordx4 v[206:207], off
	v_lshl_add_u64 v[206:207], v[216:217], 0, v[206:207]
	s_waitcnt lgkmcnt(7)
	v_mfma_f32_32x32x16_bf16 v[80:95], v[170:173], v[178:181], v[80:95]
	s_add_u32 m0, s20, 0x2000
	s_nop 0
	global_load_lds_dwordx4 v[208:209], off
	v_lshl_add_u64 v[208:209], v[216:217], 0, v[208:209]
	s_waitcnt lgkmcnt(6)
	v_mfma_f32_32x32x16_bf16 v[64:79], v[174:177], v[178:181], v[64:79]
	s_add_u32 m0, s20, 0x3000
	s_nop 0
	global_load_lds_dwordx4 v[210:211], off
	v_lshl_add_u64 v[210:211], v[216:217], 0, v[210:211]
	v_mfma_f32_32x32x16_bf16 v[48:63], v[162:165], v[200:203], v[48:63]
	s_add_u32 m0, s20, 0x4000
	s_nop 0
	global_load_lds_dwordx4 v[212:213], off
	v_lshl_add_u64 v[212:213], v[216:217], 0, v[212:213]
	v_mfma_f32_32x32x16_bf16 v[32:47], v[166:169], v[200:203], v[32:47]
	s_add_u32 m0, s20, 0x5000
	s_nop 0
	global_load_lds_dwordx4 v[214:215], off
	v_lshl_add_u64 v[214:215], v[216:217], 0, v[214:215]
	v_mfma_f32_32x32x16_bf16 v[16:31], v[170:173], v[200:203], v[16:31]
	v_mfma_f32_32x32x16_bf16 v[0:15], v[174:177], v[200:203], v[0:15]
	s_waitcnt lgkmcnt(4)
	v_mfma_f32_32x32x16_bf16 v[112:127], v[128:131], v[148:151], v[112:127]
	s_waitcnt lgkmcnt(3)
	v_mfma_f32_32x32x16_bf16 v[96:111], v[136:139], v[148:151], v[96:111]
	s_waitcnt lgkmcnt(1)
	v_mfma_f32_32x32x16_bf16 v[80:95], v[140:143], v[148:151], v[80:95]
	s_waitcnt lgkmcnt(0)
	v_mfma_f32_32x32x16_bf16 v[64:79], v[144:147], v[148:151], v[64:79]
	v_mfma_f32_32x32x16_bf16 v[48:63], v[128:131], v[132:135], v[48:63]
	v_mfma_f32_32x32x16_bf16 v[32:47], v[136:139], v[132:135], v[32:47]
	v_mfma_f32_32x32x16_bf16 v[16:31], v[140:143], v[132:135], v[16:31]
	v_mfma_f32_32x32x16_bf16 v[0:15], v[144:147], v[132:135], v[0:15]
	s_waitcnt vmcnt(6)
	s_waitcnt lgkmcnt(0)
	s_barrier
	ds_read_b128 v[162:165], v157 offset:57344
	ds_read_b128 v[178:181], v161 offset:49152
	ds_read_b128 v[166:169], v157 offset:59392
	ds_read_b128 v[200:203], v161 offset:51200
	ds_read_b128 v[170:173], v157 offset:61440
	ds_read_b128 v[174:177], v157 offset:63488
	ds_read_b128 v[128:131], v159 offset:57344
	ds_read_b128 v[148:151], v158 offset:49152
	ds_read_b128 v[136:139], v159 offset:59392
	ds_read_b128 v[132:135], v158 offset:51200
	ds_read_b128 v[140:143], v159 offset:61440
	ds_read_b128 v[144:147], v159 offset:63488
	s_waitcnt lgkmcnt(10)
	v_mfma_f32_32x32x16_bf16 v[112:127], v[162:165], v[178:181], v[112:127]
	s_add_u32 m0, s20, 0x6000
	s_nop 0
	global_load_lds_dwordx4 v[204:205], off
	v_lshl_add_u64 v[204:205], v[216:217], 0, v[204:205]
	s_waitcnt lgkmcnt(9)
	v_mfma_f32_32x32x16_bf16 v[96:111], v[166:169], v[178:181], v[96:111]
	s_add_u32 m0, s20, 0x7000
	s_nop 0
	global_load_lds_dwordx4 v[206:207], off
	v_lshl_add_u64 v[206:207], v[216:217], 0, v[206:207]
	s_waitcnt lgkmcnt(7)
	v_mfma_f32_32x32x16_bf16 v[80:95], v[170:173], v[178:181], v[80:95]
	s_add_u32 m0, s20, 0x8000
	s_nop 0
	global_load_lds_dwordx4 v[208:209], off
	v_lshl_add_u64 v[208:209], v[216:217], 0, v[208:209]
	s_waitcnt lgkmcnt(6)
	v_mfma_f32_32x32x16_bf16 v[64:79], v[174:177], v[178:181], v[64:79]
	s_add_u32 m0, s20, 0x9000
	s_nop 0
	global_load_lds_dwordx4 v[210:211], off
	v_lshl_add_u64 v[210:211], v[216:217], 0, v[210:211]
	v_mfma_f32_32x32x16_bf16 v[48:63], v[162:165], v[200:203], v[48:63]
	s_add_u32 m0, s20, 0xa000
	s_nop 0
	global_load_lds_dwordx4 v[212:213], off
	v_lshl_add_u64 v[212:213], v[216:217], 0, v[212:213]
	v_mfma_f32_32x32x16_bf16 v[32:47], v[166:169], v[200:203], v[32:47]
	s_add_u32 m0, s20, 0xb000
	s_nop 0
	global_load_lds_dwordx4 v[214:215], off
	v_lshl_add_u64 v[214:215], v[216:217], 0, v[214:215]
	v_mfma_f32_32x32x16_bf16 v[16:31], v[170:173], v[200:203], v[16:31]
	v_mfma_f32_32x32x16_bf16 v[0:15], v[174:177], v[200:203], v[0:15]
	s_waitcnt lgkmcnt(4)
	v_mfma_f32_32x32x16_bf16 v[112:127], v[128:131], v[148:151], v[112:127]
	s_waitcnt lgkmcnt(3)
	v_mfma_f32_32x32x16_bf16 v[96:111], v[136:139], v[148:151], v[96:111]
	s_waitcnt lgkmcnt(1)
	v_mfma_f32_32x32x16_bf16 v[80:95], v[140:143], v[148:151], v[80:95]
	s_waitcnt lgkmcnt(0)
	v_mfma_f32_32x32x16_bf16 v[64:79], v[144:147], v[148:151], v[64:79]
	v_mfma_f32_32x32x16_bf16 v[48:63], v[128:131], v[132:135], v[48:63]
	v_mfma_f32_32x32x16_bf16 v[32:47], v[136:139], v[132:135], v[32:47]
	v_mfma_f32_32x32x16_bf16 v[16:31], v[140:143], v[132:135], v[16:31]
	v_mfma_f32_32x32x16_bf16 v[0:15], v[144:147], v[132:135], v[0:15]
	s_waitcnt vmcnt(6)
	s_waitcnt lgkmcnt(0)
	s_barrier
	ds_read_b128 v[162:165], v157 offset:8192
	ds_read_b128 v[178:181], v161
	ds_read_b128 v[166:169], v157 offset:10240
	ds_read_b128 v[200:203], v161 offset:2048
	ds_read_b128 v[170:173], v157 offset:12288
	ds_read_b128 v[174:177], v157 offset:14336
	ds_read_b128 v[128:131], v159 offset:8192
	ds_read_b128 v[148:151], v158
	ds_read_b128 v[136:139], v159 offset:10240
	ds_read_b128 v[132:135], v158 offset:2048
	ds_read_b128 v[140:143], v159 offset:12288
	ds_read_b128 v[144:147], v159 offset:14336
	s_waitcnt lgkmcnt(10)
	v_mfma_f32_32x32x16_bf16 v[112:127], v[162:165], v[178:181], v[112:127]
	s_add_u32 m0, s20, 0xc000
	s_nop 0
	global_load_lds_dwordx4 v[204:205], off
	v_lshl_add_u64 v[204:205], v[216:217], 0, v[204:205]
	s_waitcnt lgkmcnt(9)
	v_mfma_f32_32x32x16_bf16 v[96:111], v[166:169], v[178:181], v[96:111]
	s_add_u32 m0, s20, 0xd000
	s_nop 0
	global_load_lds_dwordx4 v[206:207], off
	v_lshl_add_u64 v[206:207], v[216:217], 0, v[206:207]
	s_waitcnt lgkmcnt(7)
	v_mfma_f32_32x32x16_bf16 v[80:95], v[170:173], v[178:181], v[80:95]
	s_add_u32 m0, s20, 0xe000
	s_nop 0
	global_load_lds_dwordx4 v[208:209], off
	v_lshl_add_u64 v[208:209], v[216:217], 0, v[208:209]
	s_waitcnt lgkmcnt(6)
	v_mfma_f32_32x32x16_bf16 v[64:79], v[174:177], v[178:181], v[64:79]
	s_add_u32 m0, s20, 0xf000
	s_nop 0
	global_load_lds_dwordx4 v[210:211], off
	v_lshl_add_u64 v[210:211], v[216:217], 0, v[210:211]
	v_mfma_f32_32x32x16_bf16 v[48:63], v[162:165], v[200:203], v[48:63]
	s_add_u32 m0, s20, 0x10000
	s_nop 0
	global_load_lds_dwordx4 v[212:213], off
	v_lshl_add_u64 v[212:213], v[216:217], 0, v[212:213]
	v_mfma_f32_32x32x16_bf16 v[32:47], v[166:169], v[200:203], v[32:47]
	s_add_u32 m0, s20, 0x11000
	s_nop 0
	global_load_lds_dwordx4 v[214:215], off
	v_lshl_add_u64 v[214:215], v[216:217], 0, v[214:215]
	v_mfma_f32_32x32x16_bf16 v[16:31], v[170:173], v[200:203], v[16:31]
	v_mfma_f32_32x32x16_bf16 v[0:15], v[174:177], v[200:203], v[0:15]
	s_waitcnt lgkmcnt(4)
	v_mfma_f32_32x32x16_bf16 v[112:127], v[128:131], v[148:151], v[112:127]
	s_waitcnt lgkmcnt(3)
	v_mfma_f32_32x32x16_bf16 v[96:111], v[136:139], v[148:151], v[96:111]
	s_waitcnt lgkmcnt(1)
	v_mfma_f32_32x32x16_bf16 v[80:95], v[140:143], v[148:151], v[80:95]
	s_waitcnt lgkmcnt(0)
	v_mfma_f32_32x32x16_bf16 v[64:79], v[144:147], v[148:151], v[64:79]
	v_mfma_f32_32x32x16_bf16 v[48:63], v[128:131], v[132:135], v[48:63]
	v_mfma_f32_32x32x16_bf16 v[32:47], v[136:139], v[132:135], v[32:47]
	v_mfma_f32_32x32x16_bf16 v[16:31], v[140:143], v[132:135], v[16:31]
	v_mfma_f32_32x32x16_bf16 v[0:15], v[144:147], v[132:135], v[0:15]
	s_waitcnt vmcnt(6)
	s_waitcnt lgkmcnt(0)
	s_barrier
	s_add_u32 s18, s18, 1
	s_cmp_lg_u32 s18, 9
	s_cbranch_scc1 .Lr0_dma_loop
	ds_read_b128 v[162:165], v157 offset:32768
	ds_read_b128 v[178:181], v161 offset:24576
	ds_read_b128 v[166:169], v157 offset:34816
	ds_read_b128 v[200:203], v161 offset:26624
	ds_read_b128 v[170:173], v157 offset:36864
	ds_read_b128 v[174:177], v157 offset:38912
	ds_read_b128 v[128:131], v159 offset:32768
	ds_read_b128 v[148:151], v158 offset:24576
	ds_read_b128 v[136:139], v159 offset:34816
	ds_read_b128 v[132:135], v158 offset:26624
	ds_read_b128 v[140:143], v159 offset:36864
	ds_read_b128 v[144:147], v159 offset:38912
	s_waitcnt lgkmcnt(10)
	v_mfma_f32_32x32x16_bf16 v[112:127], v[162:165], v[178:181], v[112:127]
	s_mov_b32 m0, s20
	s_nop 0
	global_load_lds_dwordx4 v[204:205], off
	v_lshl_add_u64 v[204:205], v[216:217], 0, v[204:205]
	s_waitcnt lgkmcnt(9)
	v_mfma_f32_32x32x16_bf16 v[96:111], v[166:169], v[178:181], v[96:111]
	s_add_u32 m0, s20, 0x1000
	s_nop 0
	global_load_lds_dwordx4 v[206:207], off
	v_lshl_add_u64 v[206:207], v[216:217], 0, v[206:207]
	s_waitcnt lgkmcnt(7)
	v_mfma_f32_32x32x16_bf16 v[80:95], v[170:173], v[178:181], v[80:95]
	s_add_u32 m0, s20, 0x2000
	s_nop 0
	global_load_lds_dwordx4 v[208:209], off
	v_lshl_add_u64 v[208:209], v[216:217], 0, v[208:209]
	s_waitcnt lgkmcnt(6)
	v_mfma_f32_32x32x16_bf16 v[64:79], v[174:177], v[178:181], v[64:79]
	s_add_u32 m0, s20, 0x3000
	s_nop 0
	global_load_lds_dwordx4 v[210:211], off
	v_lshl_add_u64 v[210:211], v[216:217], 0, v[210:211]
	v_mfma_f32_32x32x16_bf16 v[48:63], v[162:165], v[200:203], v[48:63]
	s_add_u32 m0, s20, 0x4000
	s_nop 0
	global_load_lds_dwordx4 v[212:213], off
	v_lshl_add_u64 v[212:213], v[216:217], 0, v[212:213]
	v_mfma_f32_32x32x16_bf16 v[32:47], v[166:169], v[200:203], v[32:47]
	s_add_u32 m0, s20, 0x5000
	s_nop 0
	global_load_lds_dwordx4 v[214:215], off
	v_lshl_add_u64 v[214:215], v[216:217], 0, v[214:215]
	v_mfma_f32_32x32x16_bf16 v[16:31], v[170:173], v[200:203], v[16:31]
	v_mfma_f32_32x32x16_bf16 v[0:15], v[174:177], v[200:203], v[0:15]
	s_waitcnt lgkmcnt(4)
	v_mfma_f32_32x32x16_bf16 v[112:127], v[128:131], v[148:151], v[112:127]
	s_waitcnt lgkmcnt(3)
	v_mfma_f32_32x32x16_bf16 v[96:111], v[136:139], v[148:151], v[96:111]
	s_waitcnt lgkmcnt(1)
	v_mfma_f32_32x32x16_bf16 v[80:95], v[140:143], v[148:151], v[80:95]
	s_waitcnt lgkmcnt(0)
	v_mfma_f32_32x32x16_bf16 v[64:79], v[144:147], v[148:151], v[64:79]
	v_mfma_f32_32x32x16_bf16 v[48:63], v[128:131], v[132:135], v[48:63]
	v_mfma_f32_32x32x16_bf16 v[32:47], v[136:139], v[132:135], v[32:47]
	v_mfma_f32_32x32x16_bf16 v[16:31], v[140:143], v[132:135], v[16:31]
	v_mfma_f32_32x32x16_bf16 v[0:15], v[144:147], v[132:135], v[0:15]
	s_waitcnt vmcnt(6)
	s_waitcnt lgkmcnt(0)
	s_barrier
	ds_read_b128 v[162:165], v157 offset:57344
	ds_read_b128 v[178:181], v161 offset:49152
	ds_read_b128 v[166:169], v157 offset:59392
	ds_read_b128 v[200:203], v161 offset:51200
	ds_read_b128 v[170:173], v157 offset:61440
	ds_read_b128 v[174:177], v157 offset:63488
	ds_read_b128 v[128:131], v159 offset:57344
	ds_read_b128 v[148:151], v158 offset:49152
	ds_read_b128 v[136:139], v159 offset:59392
	ds_read_b128 v[132:135], v158 offset:51200
	ds_read_b128 v[140:143], v159 offset:61440
	ds_read_b128 v[144:147], v159 offset:63488
	s_waitcnt lgkmcnt(10)
	v_mfma_f32_32x32x16_bf16 v[112:127], v[162:165], v[178:181], v[112:127]
	s_add_u32 m0, s20, 0x6000
	s_nop 0
	global_load_lds_dwordx4 v[204:205], off
	v_lshl_add_u64 v[204:205], v[216:217], 0, v[204:205]
	s_waitcnt lgkmcnt(9)
	v_mfma_f32_32x32x16_bf16 v[96:111], v[166:169], v[178:181], v[96:111]
	s_add_u32 m0, s20, 0x7000
	s_nop 0
	global_load_lds_dwordx4 v[206:207], off
	v_lshl_add_u64 v[206:207], v[216:217], 0, v[206:207]
	s_waitcnt lgkmcnt(7)
	v_mfma_f32_32x32x16_bf16 v[80:95], v[170:173], v[178:181], v[80:95]
	s_add_u32 m0, s20, 0x8000
	s_nop 0
	global_load_lds_dwordx4 v[208:209], off
	v_lshl_add_u64 v[208:209], v[216:217], 0, v[208:209]
	s_waitcnt lgkmcnt(6)
	v_mfma_f32_32x32x16_bf16 v[64:79], v[174:177], v[178:181], v[64:79]
	s_add_u32 m0, s20, 0x9000
	s_nop 0
	global_load_lds_dwordx4 v[210:211], off
	v_lshl_add_u64 v[210:211], v[216:217], 0, v[210:211]
	v_mfma_f32_32x32x16_bf16 v[48:63], v[162:165], v[200:203], v[48:63]
	s_add_u32 m0, s20, 0xa000
	s_nop 0
	global_load_lds_dwordx4 v[212:213], off
	v_lshl_add_u64 v[212:213], v[216:217], 0, v[212:213]
	v_mfma_f32_32x32x16_bf16 v[32:47], v[166:169], v[200:203], v[32:47]
	s_add_u32 m0, s20, 0xb000
	s_nop 0
	global_load_lds_dwordx4 v[214:215], off
	v_lshl_add_u64 v[214:215], v[216:217], 0, v[214:215]
	v_mfma_f32_32x32x16_bf16 v[16:31], v[170:173], v[200:203], v[16:31]
	v_mfma_f32_32x32x16_bf16 v[0:15], v[174:177], v[200:203], v[0:15]
	s_waitcnt lgkmcnt(4)
	v_mfma_f32_32x32x16_bf16 v[112:127], v[128:131], v[148:151], v[112:127]
	s_waitcnt lgkmcnt(3)
	v_mfma_f32_32x32x16_bf16 v[96:111], v[136:139], v[148:151], v[96:111]
	s_waitcnt lgkmcnt(1)
	v_mfma_f32_32x32x16_bf16 v[80:95], v[140:143], v[148:151], v[80:95]
	s_waitcnt lgkmcnt(0)
	v_mfma_f32_32x32x16_bf16 v[64:79], v[144:147], v[148:151], v[64:79]
	v_mfma_f32_32x32x16_bf16 v[48:63], v[128:131], v[132:135], v[48:63]
	v_mfma_f32_32x32x16_bf16 v[32:47], v[136:139], v[132:135], v[32:47]
	v_mfma_f32_32x32x16_bf16 v[16:31], v[140:143], v[132:135], v[16:31]
	v_mfma_f32_32x32x16_bf16 v[0:15], v[144:147], v[132:135], v[0:15]
	s_waitcnt vmcnt(6)
	s_waitcnt lgkmcnt(0)
	s_barrier
	ds_read_b128 v[162:165], v157 offset:8192
	ds_read_b128 v[178:181], v161
	ds_read_b128 v[166:169], v157 offset:10240
	ds_read_b128 v[200:203], v161 offset:2048
	ds_read_b128 v[170:173], v157 offset:12288
	ds_read_b128 v[174:177], v157 offset:14336
	ds_read_b128 v[128:131], v159 offset:8192
	ds_read_b128 v[148:151], v158
	ds_read_b128 v[136:139], v159 offset:10240
	ds_read_b128 v[132:135], v158 offset:2048
	ds_read_b128 v[140:143], v159 offset:12288
	ds_read_b128 v[144:147], v159 offset:14336
	s_waitcnt lgkmcnt(10)
	v_mfma_f32_32x32x16_bf16 v[112:127], v[162:165], v[178:181], v[112:127]
	s_waitcnt lgkmcnt(9)
	v_mfma_f32_32x32x16_bf16 v[96:111], v[166:169], v[178:181], v[96:111]
	s_waitcnt lgkmcnt(7)
	v_mfma_f32_32x32x16_bf16 v[80:95], v[170:173], v[178:181], v[80:95]
	s_waitcnt lgkmcnt(6)
	v_mfma_f32_32x32x16_bf16 v[64:79], v[174:177], v[178:181], v[64:79]
	v_mfma_f32_32x32x16_bf16 v[48:63], v[162:165], v[200:203], v[48:63]
	v_mfma_f32_32x32x16_bf16 v[32:47], v[166:169], v[200:203], v[32:47]
	v_mfma_f32_32x32x16_bf16 v[16:31], v[170:173], v[200:203], v[16:31]
	v_mfma_f32_32x32x16_bf16 v[0:15], v[174:177], v[200:203], v[0:15]
	s_waitcnt lgkmcnt(4)
	v_mfma_f32_32x32x16_bf16 v[112:127], v[128:131], v[148:151], v[112:127]
	s_waitcnt lgkmcnt(3)
	v_mfma_f32_32x32x16_bf16 v[96:111], v[136:139], v[148:151], v[96:111]
	s_waitcnt lgkmcnt(1)
	v_mfma_f32_32x32x16_bf16 v[80:95], v[140:143], v[148:151], v[80:95]
	s_waitcnt lgkmcnt(0)
	v_mfma_f32_32x32x16_bf16 v[64:79], v[144:147], v[148:151], v[64:79]
	v_mfma_f32_32x32x16_bf16 v[48:63], v[128:131], v[132:135], v[48:63]
	v_mfma_f32_32x32x16_bf16 v[32:47], v[136:139], v[132:135], v[32:47]
	v_mfma_f32_32x32x16_bf16 v[16:31], v[140:143], v[132:135], v[16:31]
	v_mfma_f32_32x32x16_bf16 v[0:15], v[144:147], v[132:135], v[0:15]
	s_waitcnt vmcnt(0)
	s_waitcnt lgkmcnt(0)
	s_barrier
	ds_read_b128 v[162:165], v157 offset:32768
	ds_read_b128 v[178:181], v161 offset:24576
	ds_read_b128 v[166:169], v157 offset:34816
	ds_read_b128 v[200:203], v161 offset:26624
	ds_read_b128 v[170:173], v157 offset:36864
	ds_read_b128 v[174:177], v157 offset:38912
	ds_read_b128 v[128:131], v159 offset:32768
	ds_read_b128 v[148:151], v158 offset:24576
	ds_read_b128 v[136:139], v159 offset:34816
	ds_read_b128 v[132:135], v158 offset:26624
	ds_read_b128 v[140:143], v159 offset:36864
	ds_read_b128 v[144:147], v159 offset:38912
	s_waitcnt lgkmcnt(10)
	v_mfma_f32_32x32x16_bf16 v[112:127], v[162:165], v[178:181], v[112:127]
	s_waitcnt lgkmcnt(9)
	v_mfma_f32_32x32x16_bf16 v[96:111], v[166:169], v[178:181], v[96:111]
	s_waitcnt lgkmcnt(7)
	v_mfma_f32_32x32x16_bf16 v[80:95], v[170:173], v[178:181], v[80:95]
	s_waitcnt lgkmcnt(6)
	v_mfma_f32_32x32x16_bf16 v[64:79], v[174:177], v[178:181], v[64:79]
	v_mfma_f32_32x32x16_bf16 v[48:63], v[162:165], v[200:203], v[48:63]
	v_mfma_f32_32x32x16_bf16 v[32:47], v[166:169], v[200:203], v[32:47]
	v_mfma_f32_32x32x16_bf16 v[16:31], v[170:173], v[200:203], v[16:31]
	v_mfma_f32_32x32x16_bf16 v[0:15], v[174:177], v[200:203], v[0:15]
	s_waitcnt lgkmcnt(4)
	v_mfma_f32_32x32x16_bf16 v[112:127], v[128:131], v[148:151], v[112:127]
	s_waitcnt lgkmcnt(3)
	v_mfma_f32_32x32x16_bf16 v[96:111], v[136:139], v[148:151], v[96:111]
	s_waitcnt lgkmcnt(1)
	v_mfma_f32_32x32x16_bf16 v[80:95], v[140:143], v[148:151], v[80:95]
	s_waitcnt lgkmcnt(0)
	v_mfma_f32_32x32x16_bf16 v[64:79], v[144:147], v[148:151], v[64:79]
	s_mov_b32 s20, 0x1344000
	s_waitcnt lgkmcnt(0)
	s_barrier
	v_mfma_f32_32x32x16_bf16 v[48:63], v[128:131], v[132:135], v[48:63]
	v_ashrrev_i32_e32 v128, 1, v156
	v_and_b32_e32 v128, 0xffffffc0, v128
	v_add_u32_e32 v128, s46, v128
	v_mfma_f32_32x32x16_bf16 v[32:47], v[136:139], v[132:135], v[32:47]
	v_and_or_b32 v136, v156, 31, v128
	v_cmp_lt_i32_e32 vcc, s57, v136
	v_mfma_f32_32x32x16_bf16 v[16:31], v[140:143], v[132:135], v[16:31]
	v_mfma_f32_32x32x16_bf16 v[0:15], v[144:147], v[132:135], v[0:15]
	s_and_saveexec_b64 s[18:19], vcc
	s_xor_b64 s[18:19], exec, s[18:19]
	v_add_u32_e32 v190, 0xffffc000, v136
	v_mov_b64_e32 v[128:129], v[190:191]
	s_or_saveexec_b64 s[18:19], s[18:19]
	v_mov_b32_e32 v134, 0
	v_mov_b64_e32 v[132:133], 0
	v_mov_b64_e32 v[130:131], s[14:15]
	s_xor_b64 exec, exec, s[18:19]
	v_add_u32_e32 v128, s44, v136
	v_ashrrev_i32_e32 v129, 12, v128
	v_add_u32_e32 v134, 1, v129
	v_ashrrev_i32_e32 v129, 31, v128
	v_mov_b64_e32 v[132:133], 0x400000
	v_mov_b64_e32 v[130:131], s[4:5]
	s_or_b64 exec, exec, s[18:19]
	v_lshlrev_b32_e32 v133, 1, v156
	v_lshrrev_b32_e32 v135, 3, v156
	s_lshl_b32 s18, s45, 8
	v_and_b32_e32 v133, 0x80, v133
	v_and_b32_e32 v135, 4, v135
	v_or3_b32 v138, v135, v133, s18
	v_readlane_b32 s18, v252, 0
	v_readlane_b32 s19, v252, 1
	v_readlane_b32 s60, v252, 4
	v_add_u32_e32 v133, s2, v134
	v_mov_b64_e32 v[134:135], s[18:19]
	v_lshlrev_b32_e32 v190, 2, v132
	v_readlane_b32 s72, v252, 16
	v_readlane_b32 s73, v252, 17
	v_mad_i64_i32 v[140:141], s[18:19], v133, s88, v[134:135]
	s_nop 0
	v_lshl_add_u64 v[132:133], s[72:73], 0, v[190:191]
	v_lshlrev_b64 v[128:129], 12, v[128:129]
	v_cndmask_b32_e64 v131, v133, v131, s[40:41]
	v_cndmask_b32_e64 v130, v132, v130, s[40:41]
	v_ashrrev_i32_e32 v139, 31, v138
	v_lshl_add_u64 v[142:143], v[132:133], 0, v[128:129]
	v_lshl_add_u64 v[130:131], v[130:131], 0, v[128:129]
	v_lshlrev_b64 v[128:129], 2, v[138:139]
	v_lshl_add_u64 v[134:135], v[130:131], 0, v[128:129]
	v_lshl_add_u64 v[132:133], v[140:141], 0, v[128:129]
	v_lshl_add_u64 v[130:131], v[142:143], 0, v[128:129]
	flat_load_dwordx4 v[138:141], v[134:135]
	global_load_dwordx4 v[142:145], v[132:133], off
	v_readlane_b32 s61, v252, 5
	v_readlane_b32 s62, v252, 6
	v_readlane_b32 s63, v252, 7
	v_readlane_b32 s64, v252, 8
	v_readlane_b32 s65, v252, 9
	v_readlane_b32 s66, v252, 10
	v_readlane_b32 s67, v252, 11
	v_readlane_b32 s68, v252, 12
	v_readlane_b32 s69, v252, 13
	v_readlane_b32 s70, v252, 14
	v_readlane_b32 s71, v252, 15
	v_readlane_b32 s74, v252, 18
	v_readlane_b32 s75, v252, 19
	s_waitcnt vmcnt(0) lgkmcnt(0)
	v_pk_fma_f32 v[112:113], v[112:113], v[142:143], v[138:139]
	v_pk_fma_f32 v[114:115], v[114:115], v[144:145], v[140:141]
	global_store_dwordx4 v[130:131], v[112:115], off
	flat_load_dwordx4 v[112:115], v[134:135] offset:32
	s_nop 0
	global_load_dwordx4 v[138:141], v[132:133], off offset:32
	s_waitcnt vmcnt(0) lgkmcnt(0)
	v_pk_fma_f32 v[112:113], v[116:117], v[138:139], v[112:113]
	v_pk_fma_f32 v[114:115], v[118:119], v[140:141], v[114:115]
	global_store_dwordx4 v[130:131], v[112:115], off offset:32
	flat_load_dwordx4 v[112:115], v[134:135] offset:64
	s_nop 0
	global_load_dwordx4 v[116:119], v[132:133], off offset:64
	s_waitcnt vmcnt(0) lgkmcnt(0)
	v_pk_fma_f32 v[112:113], v[120:121], v[116:117], v[112:113]
	v_pk_fma_f32 v[114:115], v[122:123], v[118:119], v[114:115]
	global_store_dwordx4 v[130:131], v[112:115], off offset:64
	flat_load_dwordx4 v[112:115], v[134:135] offset:96
	s_nop 0
	global_load_dwordx4 v[116:119], v[132:133], off offset:96
	s_waitcnt vmcnt(0) lgkmcnt(0)
	v_pk_fma_f32 v[112:113], v[124:125], v[116:117], v[112:113]
	v_pk_fma_f32 v[114:115], v[126:127], v[118:119], v[114:115]
	global_store_dwordx4 v[130:131], v[112:115], off offset:96
	flat_load_dwordx4 v[112:115], v[134:135] offset:128
	s_nop 0
	global_load_dwordx4 v[116:119], v[132:133], off offset:128
	s_waitcnt vmcnt(0) lgkmcnt(0)
	v_pk_fma_f32 v[96:97], v[96:97], v[116:117], v[112:113]
	v_pk_fma_f32 v[98:99], v[98:99], v[118:119], v[114:115]
	global_store_dwordx4 v[130:131], v[96:99], off offset:128
	flat_load_dwordx4 v[96:99], v[134:135] offset:160
	s_nop 0
	global_load_dwordx4 v[112:115], v[132:133], off offset:160
	s_waitcnt vmcnt(0) lgkmcnt(0)
	v_pk_fma_f32 v[96:97], v[100:101], v[112:113], v[96:97]
	v_pk_fma_f32 v[98:99], v[102:103], v[114:115], v[98:99]
	global_store_dwordx4 v[130:131], v[96:99], off offset:160
	flat_load_dwordx4 v[96:99], v[134:135] offset:192
	s_nop 0
	global_load_dwordx4 v[100:103], v[132:133], off offset:192
	s_waitcnt vmcnt(0) lgkmcnt(0)
	v_pk_fma_f32 v[96:97], v[104:105], v[100:101], v[96:97]
	v_pk_fma_f32 v[98:99], v[106:107], v[102:103], v[98:99]
	global_store_dwordx4 v[130:131], v[96:99], off offset:192
	flat_load_dwordx4 v[96:99], v[134:135] offset:224
	s_nop 0
	global_load_dwordx4 v[100:103], v[132:133], off offset:224
	s_waitcnt vmcnt(0) lgkmcnt(0)
	v_pk_fma_f32 v[96:97], v[108:109], v[100:101], v[96:97]
	v_pk_fma_f32 v[98:99], v[110:111], v[102:103], v[98:99]
	global_store_dwordx4 v[130:131], v[96:99], off offset:224
	flat_load_dwordx4 v[96:99], v[134:135] offset:256
	s_nop 0
	global_load_dwordx4 v[100:103], v[132:133], off offset:256
	s_waitcnt vmcnt(0) lgkmcnt(0)
	v_pk_fma_f32 v[80:81], v[80:81], v[100:101], v[96:97]
	v_pk_fma_f32 v[82:83], v[82:83], v[102:103], v[98:99]
	global_store_dwordx4 v[130:131], v[80:83], off offset:256
	flat_load_dwordx4 v[80:83], v[134:135] offset:288
	s_nop 0
	global_load_dwordx4 v[96:99], v[132:133], off offset:288
	s_waitcnt vmcnt(0) lgkmcnt(0)
	v_pk_fma_f32 v[80:81], v[84:85], v[96:97], v[80:81]
	v_pk_fma_f32 v[82:83], v[86:87], v[98:99], v[82:83]
	global_store_dwordx4 v[130:131], v[80:83], off offset:288
	flat_load_dwordx4 v[80:83], v[134:135] offset:320
	s_nop 0
	global_load_dwordx4 v[84:87], v[132:133], off offset:320
	s_waitcnt vmcnt(0) lgkmcnt(0)
	v_pk_fma_f32 v[80:81], v[88:89], v[84:85], v[80:81]
	v_pk_fma_f32 v[82:83], v[90:91], v[86:87], v[82:83]
	global_store_dwordx4 v[130:131], v[80:83], off offset:320
	flat_load_dwordx4 v[80:83], v[134:135] offset:352
	s_nop 0
	global_load_dwordx4 v[84:87], v[132:133], off offset:352
	s_waitcnt vmcnt(0) lgkmcnt(0)
	v_pk_fma_f32 v[80:81], v[92:93], v[84:85], v[80:81]
	v_pk_fma_f32 v[82:83], v[94:95], v[86:87], v[82:83]
	global_store_dwordx4 v[130:131], v[80:83], off offset:352
	flat_load_dwordx4 v[80:83], v[134:135] offset:384
	s_nop 0
	global_load_dwordx4 v[84:87], v[132:133], off offset:384
	s_waitcnt vmcnt(0) lgkmcnt(0)
	v_pk_fma_f32 v[64:65], v[64:65], v[84:85], v[80:81]
	v_pk_fma_f32 v[66:67], v[66:67], v[86:87], v[82:83]
	global_store_dwordx4 v[130:131], v[64:67], off offset:384
	flat_load_dwordx4 v[64:67], v[134:135] offset:416
	s_nop 0
	global_load_dwordx4 v[80:83], v[132:133], off offset:416
	s_waitcnt vmcnt(0) lgkmcnt(0)
	v_pk_fma_f32 v[64:65], v[68:69], v[80:81], v[64:65]
	v_pk_fma_f32 v[66:67], v[70:71], v[82:83], v[66:67]
	global_store_dwordx4 v[130:131], v[64:67], off offset:416
	flat_load_dwordx4 v[64:67], v[134:135] offset:448
	s_nop 0
	global_load_dwordx4 v[68:71], v[132:133], off offset:448
	s_waitcnt vmcnt(0) lgkmcnt(0)
	v_pk_fma_f32 v[64:65], v[72:73], v[68:69], v[64:65]
	v_pk_fma_f32 v[66:67], v[74:75], v[70:71], v[66:67]
	global_store_dwordx4 v[130:131], v[64:67], off offset:448
	flat_load_dwordx4 v[64:67], v[134:135] offset:480
	s_nop 0
	global_load_dwordx4 v[68:71], v[132:133], off offset:480
	s_waitcnt vmcnt(0) lgkmcnt(0)
	v_pk_fma_f32 v[66:67], v[78:79], v[70:71], v[66:67]
	v_or_b32_e32 v70, 32, v136
	v_pk_fma_f32 v[64:65], v[76:77], v[68:69], v[64:65]
	v_cmp_lt_i32_e32 vcc, s57, v70
	global_store_dwordx4 v[130:131], v[64:67], off offset:480
	s_and_saveexec_b64 s[18:19], vcc
	s_xor_b64 s[18:19], exec, s[18:19]
	v_add_u32_e32 v190, 0xffffc020, v136
	v_mov_b64_e32 v[64:65], v[190:191]
	s_or_saveexec_b64 s[18:19], s[18:19]
	v_mov_b32_e32 v71, 0
	v_mov_b64_e32 v[68:69], 0
	v_mov_b64_e32 v[66:67], s[14:15]
	s_xor_b64 exec, exec, s[18:19]
	s_cbranch_execz .LBB0_920
	v_add_u32_e32 v64, s44, v70
	v_ashrrev_i32_e32 v65, 12, v64
	v_add_u32_e32 v71, 1, v65
	v_ashrrev_i32_e32 v65, 31, v64
	v_mov_b64_e32 v[68:69], 0x400000
	v_mov_b64_e32 v[66:67], s[4:5]
	s_branch .LBB0_920
